# attention epilogue: O tile transposed through a private LDS slice per wave, 8 x 16-byte stores per lane instead of 64 x 2-byte stores
# baseline (speedup 1.0000x reference)
; __device__ __forceinline__ unsigned short f2bf_rne(float f) { unsigned u = __float_as_uint(f); u += 0x7FFFu + ((u >> 16) & 1u); return (unsigned short)(u >> 16); }
; __device__ __forceinline__ int crow(int r, int hi) { return (r & 3) + 8 * (r >> 2) + 4 * hi; }
; template <typename TQ>
; __device__ __forceinline__ void attn_dense_body(const TQ* __restrict__ Qb, const bf16* __restrict__ Kh, const bf16* __restrict__ Vh,
;                                                 unsigned short* __restrict__ Ob, int seq, char* lds, const float* __restrict__ qg, int pos0) {
;     ...
;   if (hi == 0) li_l[r32] = l_reg; asm volatile("s_waitcnt lgkmcnt(0)" ::: "memory");
;   float rli[16];
; #pragma unroll
;   for (int r = 0; r < 16; ++r) rli[r] = __builtin_amdgcn_rcpf(li_l[crow(r, hi)]);
;   unsigned short* Ow = Ob + (long)(wid * QBLK) * LDO;
; #pragma unroll
;   for (int r = 0; r < 16; ++r) { int orow = crow(r, hi);
;     for (int d0 = 0; d0 < 4; ++d0) Ow[(long)orow * LDO + d0 * 32 + r32] = f2bf_rne(o[d0][r] * rli[r]); }
.LBB0_901:
	s_or_b64 exec, exec, s[6:7]
	s_waitcnt lgkmcnt(0)
	v_add_u32_e32 v72, v185, v182
	ds_read_b128 v[64:67], v72
	ds_read_b128 v[68:71], v72 offset:32
	s_lshl_b64 s[4:5], s[28:29], 11
	s_add_u32 s4, s30, s4
	s_addc_u32 s5, s31, s5
	s_waitcnt lgkmcnt(1)
	v_rcp_f32_e32 v73, v64
	v_rcp_f32_e32 v74, v65
	v_rcp_f32_e32 v75, v66
	v_rcp_f32_e32 v76, v67
	ds_read_b128 v[64:67], v72 offset:64
	s_lshl_b32 s6, s57, 1
	s_add_u32 s4, s4, s6
	v_ashrrev_i32_e32 v185, 31, v184
	s_addc_u32 s5, s5, 0
	s_waitcnt lgkmcnt(1)
	v_rcp_f32_e32 v77, v68
	v_rcp_f32_e32 v78, v69
	v_rcp_f32_e32 v79, v70
	v_rcp_f32_e32 v80, v71
	ds_read_b128 v[68:71], v72 offset:96
	s_waitcnt lgkmcnt(1)
	v_rcp_f32_e32 v72, v64
	v_rcp_f32_e32 v81, v65
	v_lshlrev_b64 v[64:65], 11, v[184:185]
	v_lshl_add_u64 v[64:65], s[4:5], 0, v[64:65]
	v_mov_b64_e32 v[84:85], v[64:65]
	v_and_b32_e32 v88, 63, v181
	v_lshrrev_b32_e32 v89, 6, v181
	v_mul_u32_u24_e32 v86, 8704, v89
	v_add_u32_e32 v86, 69632, v86
	v_lshrrev_b32_e32 v90, 5, v88
	v_mul_u32_u24_e32 v90, 1088, v90
	v_and_b32_e32 v91, 31, v88
	v_lshlrev_b32_e32 v91, 1, v91
	v_lshrrev_b32_e32 v92, 1, v88
	v_and_b32_e32 v93, 1, v88
	v_lshlrev_b32_e32 v93, 7, v93
	v_mul_u32_u24_e32 v87, 272, v92
	v_add3_u32 v87, v87, v86, v93
	v_add3_u32 v86, v86, v90, v91
	v_lshl_add_u32 v88, v92, 11, v93
	v_mov_b32_e32 v89, 0
	v_lshl_add_u64 v[84:85], v[84:85], 0, v[88:89]
	v_lshlrev_b32_e32 v182, 1, v197
	v_rcp_f32_e32 v82, v66
	v_rcp_f32_e32 v83, v67
	v_lshlrev_b32_e32 v66, 13, v196
	v_lshl_add_u64 v[64:65], v[64:65], 0, v[182:183]
	v_mov_b32_e32 v67, v183
	v_mul_f32_e32 v0, v0, v73
	v_lshl_add_u64 v[64:65], v[64:65], 0, v[66:67]
	v_bfe_u32 v66, v0, 16, 1
	v_add3_u32 v0, v0, v66, s49
	ds_write_b16_d16_hi v86, v0 offset:0
	v_mul_f32_e32 v0, v48, v73
	v_bfe_u32 v48, v0, 16, 1
	v_add3_u32 v0, v0, v48, s49
	ds_write_b16_d16_hi v86, v0 offset:64
	v_mul_f32_e32 v0, v32, v73
	v_bfe_u32 v32, v0, 16, 1
	v_add3_u32 v0, v0, v32, s49
	ds_write_b16_d16_hi v86, v0 offset:128
	v_mul_f32_e32 v0, v16, v73
	v_bfe_u32 v16, v0, 16, 1
	v_add3_u32 v0, v0, v16, s49
	ds_write_b16_d16_hi v86, v0 offset:192
	v_mul_f32_e32 v0, v1, v74
	v_bfe_u32 v1, v0, 16, 1
	v_add3_u32 v0, v0, v1, s49
	ds_write_b16_d16_hi v86, v0 offset:272
	v_mul_f32_e32 v0, v49, v74
	v_bfe_u32 v1, v0, 16, 1
	v_add3_u32 v0, v0, v1, s49
	ds_write_b16_d16_hi v86, v0 offset:336
	v_mul_f32_e32 v0, v33, v74
	v_bfe_u32 v1, v0, 16, 1
	v_add3_u32 v0, v0, v1, s49
	ds_write_b16_d16_hi v86, v0 offset:400
	v_mul_f32_e32 v0, v17, v74
	v_bfe_u32 v1, v0, 16, 1
	v_add3_u32 v0, v0, v1, s49
	ds_write_b16_d16_hi v86, v0 offset:464
	v_mul_f32_e32 v0, v2, v75
	v_bfe_u32 v1, v0, 16, 1
	v_add3_u32 v2, v0, v1, s49
	v_add_co_u32_e32 v0, vcc, s50, v64
	s_waitcnt lgkmcnt(0)
	v_rcp_f32_e32 v68, v68
	v_addc_co_u32_e32 v1, vcc, 0, v65, vcc
	ds_write_b16_d16_hi v86, v2 offset:544
	v_mul_f32_e32 v2, v50, v75
	v_bfe_u32 v16, v2, 16, 1
	v_add3_u32 v2, v2, v16, s49
	ds_write_b16_d16_hi v86, v2 offset:608
	v_mul_f32_e32 v2, v34, v75
	v_bfe_u32 v16, v2, 16, 1
	v_add3_u32 v2, v2, v16, s49
	ds_write_b16_d16_hi v86, v2 offset:672
	v_mul_f32_e32 v2, v18, v75
	v_bfe_u32 v16, v2, 16, 1
	v_add3_u32 v2, v2, v16, s49
	ds_write_b16_d16_hi v86, v2 offset:736
	v_mul_f32_e32 v2, v3, v76
	v_bfe_u32 v3, v2, 16, 1
	v_add3_u32 v2, v2, v3, s49
	ds_write_b16_d16_hi v86, v2 offset:816
	v_mul_f32_e32 v2, v51, v76
	v_bfe_u32 v3, v2, 16, 1
	v_add3_u32 v2, v2, v3, s49
	ds_write_b16_d16_hi v86, v2 offset:880
	v_mul_f32_e32 v2, v35, v76
	v_bfe_u32 v3, v2, 16, 1
	v_add3_u32 v2, v2, v3, s49
	ds_write_b16_d16_hi v86, v2 offset:944
	v_mul_f32_e32 v2, v19, v76
	v_bfe_u32 v3, v2, 16, 1
	v_add3_u32 v2, v2, v3, s49
	ds_write_b16_d16_hi v86, v2 offset:1008
	v_mul_f32_e32 v0, v4, v77
	v_bfe_u32 v1, v0, 16, 1
	v_add3_u32 v4, v0, v1, s49
	v_add_co_u32_e32 v0, vcc, s46, v64
	v_rcp_f32_e32 v69, v69
	s_nop 0
	v_addc_co_u32_e32 v1, vcc, 0, v65, vcc
	v_add_co_u32_e32 v2, vcc, s51, v64
	v_rcp_f32_e32 v70, v70
	s_nop 0
	v_addc_co_u32_e32 v3, vcc, 0, v65, vcc
	ds_write_b16_d16_hi v86, v4 offset:2176
	v_mul_f32_e32 v4, v52, v77
	v_bfe_u32 v16, v4, 16, 1
	v_add3_u32 v4, v4, v16, s49
	ds_write_b16_d16_hi v86, v4 offset:2240
	v_mul_f32_e32 v4, v36, v77
	v_bfe_u32 v16, v4, 16, 1
	v_add3_u32 v4, v4, v16, s49
	ds_write_b16_d16_hi v86, v4 offset:2304
	v_mul_f32_e32 v4, v20, v77
	v_bfe_u32 v16, v4, 16, 1
	v_add3_u32 v4, v4, v16, s49
	ds_write_b16_d16_hi v86, v4 offset:2368
	v_mul_f32_e32 v4, v5, v78
	v_bfe_u32 v5, v4, 16, 1
	v_add3_u32 v4, v4, v5, s49
	ds_write_b16_d16_hi v86, v4 offset:2448
	v_mul_f32_e32 v4, v53, v78
	v_bfe_u32 v5, v4, 16, 1
	v_add3_u32 v4, v4, v5, s49
	ds_write_b16_d16_hi v86, v4 offset:2512
	v_mul_f32_e32 v4, v37, v78
	v_bfe_u32 v5, v4, 16, 1
	v_add3_u32 v4, v4, v5, s49
	ds_write_b16_d16_hi v86, v4 offset:2576
	v_mul_f32_e32 v4, v21, v78
	v_bfe_u32 v5, v4, 16, 1
	v_add3_u32 v4, v4, v5, s49
	ds_write_b16_d16_hi v86, v4 offset:2640
	v_mul_f32_e32 v0, v6, v79
	v_bfe_u32 v1, v0, 16, 1
	v_add3_u32 v0, v0, v1, s49
	ds_write_b16_d16_hi v86, v0 offset:2720
	v_mul_f32_e32 v0, v54, v79
	v_bfe_u32 v1, v0, 16, 1
	v_add3_u32 v0, v0, v1, s49
	ds_write_b16_d16_hi v86, v0 offset:2784
	v_mul_f32_e32 v0, v38, v79
	v_bfe_u32 v1, v0, 16, 1
	v_add3_u32 v0, v0, v1, s49
	ds_write_b16_d16_hi v86, v0 offset:2848
	v_mul_f32_e32 v0, v22, v79
	v_bfe_u32 v1, v0, 16, 1
	v_add3_u32 v0, v0, v1, s49
	ds_write_b16_d16_hi v86, v0 offset:2912
	v_mul_f32_e32 v0, v7, v80
	v_bfe_u32 v1, v0, 16, 1
	v_add3_u32 v0, v0, v1, s49
	ds_write_b16_d16_hi v86, v0 offset:2992
	v_mul_f32_e32 v0, v55, v80
	v_bfe_u32 v1, v0, 16, 1
	v_add3_u32 v0, v0, v1, s49
	ds_write_b16_d16_hi v86, v0 offset:3056
; __device__ __forceinline__ unsigned short f2bf_rne(float f) { unsigned u = __float_as_uint(f); u += 0x7FFFu + ((u >> 16) & 1u); return (unsigned short)(u >> 16); }
; __device__ __forceinline__ int crow(int r, int hi) { return (r & 3) + 8 * (r >> 2) + 4 * hi; }
; template <typename TQ>
; __device__ __forceinline__ void attn_dense_body(const TQ* __restrict__ Qb, const bf16* __restrict__ Kh, const bf16* __restrict__ Vh,
;                                                 unsigned short* __restrict__ Ob, int seq, char* lds, const float* __restrict__ qg, int pos0) {
;     ...
;   for (int r = 0; r < 16; ++r) rli[r] = __builtin_amdgcn_rcpf(li_l[crow(r, hi)]);
;   unsigned short* Ow = Ob + (long)(wid * QBLK) * LDO;
; #pragma unroll
;   for (int r = 0; r < 16; ++r) { int orow = crow(r, hi);
;     for (int d0 = 0; d0 < 4; ++d0) Ow[(long)orow * LDO + d0 * 32 + r32] = f2bf_rne(o[d0][r] * rli[r]); }
	v_mul_f32_e32 v0, v39, v80
	v_bfe_u32 v1, v0, 16, 1
	v_add3_u32 v0, v0, v1, s49
	ds_write_b16_d16_hi v86, v0 offset:3120
	v_mul_f32_e32 v0, v23, v80
	v_bfe_u32 v1, v0, 16, 1
	v_add3_u32 v0, v0, v1, s49
	ds_write_b16_d16_hi v86, v0 offset:3184
	v_mul_f32_e32 v0, v8, v72
	v_bfe_u32 v1, v0, 16, 1
	v_add3_u32 v4, v0, v1, s49
	v_add_co_u32_e32 v0, vcc, s52, v64
	v_rcp_f32_e32 v71, v71
	s_nop 0
	v_addc_co_u32_e32 v1, vcc, 0, v65, vcc
	v_add_co_u32_e32 v2, vcc, s53, v64
	s_add_i32 s25, s25, s33
	s_nop 0
	v_addc_co_u32_e32 v3, vcc, 0, v65, vcc
	ds_write_b16_d16_hi v86, v4 offset:4352
	v_mul_f32_e32 v4, v56, v72
	v_bfe_u32 v5, v4, 16, 1
	v_add3_u32 v4, v4, v5, s49
	ds_write_b16_d16_hi v86, v4 offset:4416
	v_mul_f32_e32 v4, v40, v72
	v_bfe_u32 v5, v4, 16, 1
	v_add3_u32 v4, v4, v5, s49
	ds_write_b16_d16_hi v86, v4 offset:4480
	v_mul_f32_e32 v4, v24, v72
	v_bfe_u32 v5, v4, 16, 1
	v_add3_u32 v4, v4, v5, s49
	ds_write_b16_d16_hi v86, v4 offset:4544
	v_mul_f32_e32 v4, v9, v81
	v_bfe_u32 v5, v4, 16, 1
	v_add3_u32 v4, v4, v5, s49
	ds_write_b16_d16_hi v86, v4 offset:4624
	v_mul_f32_e32 v4, v57, v81
	v_bfe_u32 v5, v4, 16, 1
	v_add3_u32 v4, v4, v5, s49
	ds_write_b16_d16_hi v86, v4 offset:4688
	v_mul_f32_e32 v4, v41, v81
	v_bfe_u32 v5, v4, 16, 1
	v_add3_u32 v4, v4, v5, s49
	ds_write_b16_d16_hi v86, v4 offset:4752
	v_mul_f32_e32 v4, v25, v81
	v_bfe_u32 v5, v4, 16, 1
	v_add3_u32 v4, v4, v5, s49
	ds_write_b16_d16_hi v86, v4 offset:4816
	v_mul_f32_e32 v0, v10, v82
	v_bfe_u32 v1, v0, 16, 1
	v_add3_u32 v0, v0, v1, s49
	ds_write_b16_d16_hi v86, v0 offset:4896
	v_mul_f32_e32 v0, v58, v82
	v_bfe_u32 v1, v0, 16, 1
	v_add3_u32 v0, v0, v1, s49
	ds_write_b16_d16_hi v86, v0 offset:4960
	v_mul_f32_e32 v0, v42, v82
	v_bfe_u32 v1, v0, 16, 1
	v_add3_u32 v0, v0, v1, s49
	ds_write_b16_d16_hi v86, v0 offset:5024
	v_mul_f32_e32 v0, v26, v82
	v_bfe_u32 v1, v0, 16, 1
	v_add3_u32 v0, v0, v1, s49
	ds_write_b16_d16_hi v86, v0 offset:5088
	v_mul_f32_e32 v0, v11, v83
	v_bfe_u32 v1, v0, 16, 1
	v_add3_u32 v0, v0, v1, s49
	ds_write_b16_d16_hi v86, v0 offset:5168
	v_mul_f32_e32 v0, v59, v83
	v_bfe_u32 v1, v0, 16, 1
	v_add3_u32 v0, v0, v1, s49
	ds_write_b16_d16_hi v86, v0 offset:5232
	v_mul_f32_e32 v0, v43, v83
	v_bfe_u32 v1, v0, 16, 1
	v_add3_u32 v0, v0, v1, s49
	ds_write_b16_d16_hi v86, v0 offset:5296
	v_mul_f32_e32 v0, v27, v83
	v_bfe_u32 v1, v0, 16, 1
	v_add3_u32 v0, v0, v1, s49
	ds_write_b16_d16_hi v86, v0 offset:5360
	v_mul_f32_e32 v0, v12, v68
	v_bfe_u32 v1, v0, 16, 1
	v_add3_u32 v4, v0, v1, s49
	v_add_co_u32_e32 v0, vcc, s54, v64
	s_add_i32 s56, s56, 1
	s_nop 0
	v_addc_co_u32_e32 v1, vcc, 0, v65, vcc
	v_add_co_u32_e32 v2, vcc, s55, v64
	s_cmpk_lt_i32 s25, 0x200
	s_nop 0
	v_addc_co_u32_e32 v3, vcc, 0, v65, vcc
	ds_write_b16_d16_hi v86, v4 offset:6528
	v_mul_f32_e32 v4, v60, v68
	v_bfe_u32 v5, v4, 16, 1
	v_add3_u32 v4, v4, v5, s49
	ds_write_b16_d16_hi v86, v4 offset:6592
	v_mul_f32_e32 v4, v44, v68
	v_bfe_u32 v5, v4, 16, 1
	v_add3_u32 v4, v4, v5, s49
	ds_write_b16_d16_hi v86, v4 offset:6656
	v_mul_f32_e32 v4, v28, v68
	v_bfe_u32 v5, v4, 16, 1
	v_add3_u32 v4, v4, v5, s49
	ds_write_b16_d16_hi v86, v4 offset:6720
	v_mul_f32_e32 v4, v13, v69
	v_bfe_u32 v5, v4, 16, 1
	v_add3_u32 v4, v4, v5, s49
	ds_write_b16_d16_hi v86, v4 offset:6800
	v_mul_f32_e32 v4, v61, v69
	v_bfe_u32 v5, v4, 16, 1
	v_add3_u32 v4, v4, v5, s49
	ds_write_b16_d16_hi v86, v4 offset:6864
	v_mul_f32_e32 v4, v45, v69
	v_bfe_u32 v5, v4, 16, 1
	v_add3_u32 v4, v4, v5, s49
	ds_write_b16_d16_hi v86, v4 offset:6928
	v_mul_f32_e32 v4, v29, v69
	v_bfe_u32 v5, v4, 16, 1
	v_add3_u32 v4, v4, v5, s49
	ds_write_b16_d16_hi v86, v4 offset:6992
	v_mul_f32_e32 v0, v14, v70
	v_bfe_u32 v1, v0, 16, 1
	v_add3_u32 v0, v0, v1, s49
	ds_write_b16_d16_hi v86, v0 offset:7072
	v_mul_f32_e32 v0, v62, v70
	v_bfe_u32 v1, v0, 16, 1
	v_add3_u32 v0, v0, v1, s49
	ds_write_b16_d16_hi v86, v0 offset:7136
	v_mul_f32_e32 v0, v46, v70
	v_bfe_u32 v1, v0, 16, 1
	v_add3_u32 v0, v0, v1, s49
	ds_write_b16_d16_hi v86, v0 offset:7200
	v_mul_f32_e32 v0, v30, v70
	v_bfe_u32 v1, v0, 16, 1
	v_add3_u32 v0, v0, v1, s49
	ds_write_b16_d16_hi v86, v0 offset:7264
	v_mul_f32_e32 v0, v15, v71
	v_bfe_u32 v1, v0, 16, 1
	v_add3_u32 v0, v0, v1, s49
	ds_write_b16_d16_hi v86, v0 offset:7344
	v_mul_f32_e32 v0, v63, v71
	v_bfe_u32 v1, v0, 16, 1
	v_add3_u32 v0, v0, v1, s49
	ds_write_b16_d16_hi v86, v0 offset:7408
	v_mul_f32_e32 v0, v47, v71
	v_bfe_u32 v1, v0, 16, 1
	v_add3_u32 v0, v0, v1, s49
	ds_write_b16_d16_hi v86, v0 offset:7472
	v_mul_f32_e32 v0, v31, v71
	v_bfe_u32 v1, v0, 16, 1
	v_add3_u32 v0, v0, v1, s49
	ds_write_b16_d16_hi v86, v0 offset:7536
	s_waitcnt lgkmcnt(0)
	ds_read_b128 v[92:95], v87
	ds_read_b128 v[96:99], v87 offset:16
	ds_read_b128 v[100:103], v87 offset:32
	ds_read_b128 v[104:107], v87 offset:48
	ds_read_b128 v[108:111], v87 offset:64
	ds_read_b128 v[112:115], v87 offset:80
	ds_read_b128 v[116:119], v87 offset:96
	ds_read_b128 v[120:123], v87 offset:112
	s_waitcnt lgkmcnt(7)
	global_store_dwordx4 v[84:85], v[92:95], off
	s_waitcnt lgkmcnt(6)
	global_store_dwordx4 v[84:85], v[96:99], off offset:16
	s_waitcnt lgkmcnt(5)
	global_store_dwordx4 v[84:85], v[100:103], off offset:32
	s_waitcnt lgkmcnt(4)
	global_store_dwordx4 v[84:85], v[104:107], off offset:48
	s_waitcnt lgkmcnt(3)
	global_store_dwordx4 v[84:85], v[108:111], off offset:64
	s_waitcnt lgkmcnt(2)
	global_store_dwordx4 v[84:85], v[112:115], off offset:80
	s_waitcnt lgkmcnt(1)
	global_store_dwordx4 v[84:85], v[116:119], off offset:96
	s_waitcnt lgkmcnt(0)
	global_store_dwordx4 v[84:85], v[120:123], off offset:112
	s_waitcnt vmcnt(63) expcnt(7) lgkmcnt(15)
	s_barrier
	s_cbranch_scc0 .LBB0_923
